# q4c + layer-1 w_in/w_out weight transposes (1088 tiles) moved from the prepass into the idle tail of layer-0's w_in GEMM phase
# speedup vs baseline: 1.0532x; 1.0532x over previous
; __device__ __forceinline__ int bid_o() { int t = (int)blockIdx.x; asm volatile("" : "+s"(t)); return t; }
; __device__ __forceinline__ TTile tile_desc(KParams p, int it) {
;     TTile t; const int l = it / 3136; int r = it % 3136; size_t off;
;     if (r < 832) { t.W = p->w_in + (size_t)l * DM * NIN; t.K = DM; t.N = NIN; off = WT_IN; }
;     else if (r < 1088) { r -= 832; t.W = p->w_out + (size_t)l * DM * DM; t.K = DM; t.N = DM; off = WT_OUT; }
;     else if (r < 2112) { r -= 1088; t.W = p->w1 + (size_t)l * DM * HID; t.K = DM; t.N = HID; off = WT_1; }
;     else { r -= 2112; t.W = p->w2 + (size_t)l * HID * DM; t.K = HID; t.N = DM; off = WT_2; }
;     const int ntn = t.N / 128; t.tk = r / ntn; t.tn = r % ntn; t.Wt = p->wt + (size_t)l * WT_LAYER + off; return t;
; __device__ __forceinline__ void run_phase(KParams p, int ph, LAS unsigned char* lds) {
;     ...
;               if (l == 0 && bid_o() >= 80) {
;                   const int b2 = bid_o() - 80; const int n_it = (2048 - b2 + 175) / 176;
;                   transpose_tiles(p, lds, n_it, [&](int k) { return 4224 + b2 + 176 * k; }); } } break;
.LBB0_359:
	v_readlane_b32 s8, v255, 3
	v_readlane_b32 s9, v255, 4
	s_andn2_b64 vcc, exec, s[8:9]
	s_mov_b32 s98, s74
	s_waitcnt vmcnt(0) lgkmcnt(0)
	s_barrier
	s_cbranch_vccnz .LBB0_391
	s_mov_b32 s8, s94
	s_cmpk_lt_i32 s8, 0x50
	s_cbranch_scc1 .LBB0_391
	s_mov_b32 s30, s94
	s_sub_i32 s24, 0xd3f, s30
	v_mov_b32_e32 v34, v208
	s_cmpk_lt_i32 s24, 0xb0
	s_cbranch_scc1 .LBB0_391
	s_add_i32 s9, s30, 0xbf0
	s_mul_hi_i32 s8, s9, 0x5397829d
	s_lshr_b32 s10, s8, 31
	s_ashr_i32 s8, s8, 10
	s_load_dwordx2 s[48:49], s[0:1], 0xa8
	s_add_i32 s8, s8, s10
	s_mul_i32 s10, s8, 0xc40
	s_sub_i32 s41, s9, s10
	s_cmpk_gt_i32 s41, 0x33f
	s_mov_b64 s[28:29], -1
	s_cbranch_scc0 .LBB0_372
	s_cmpk_gt_u32 s41, 0x43f
	s_cbranch_scc0 .LBB0_369
	s_ashr_i32 s9, s8, 31
	s_lshl_b64 s[26:27], s[8:9], 26
	s_cmpk_gt_u32 s41, 0x83f
	s_cbranch_scc0 .LBB0_366
	s_load_dwordx2 s[10:11], s[0:1], 0x88
	s_add_i32 s40, s41, 0xfffff7c0
	s_mov_b64 s[28:29], 0
	s_waitcnt lgkmcnt(0)
	s_add_u32 s10, s10, s26
	s_addc_u32 s11, s11, s27

; #define LAS __attribute__((address_space(3)))
; __device__ __forceinline__ int tid_o() { int t = (int)threadIdx.x; asm volatile("" : "+v"(t)); return t; }
; __device__ __forceinline__ void tile_load(f32x4 (&v)[8], const TTile& t, int tid) {
;     const int kr = tid >> 5, n4 = tid & 31;
; #pragma unroll
;     for (int i = 0; i < 8; ++i) v[i] = *(const f32x4*)(t.W + (size_t)(t.tk * 128 + kr + 16 * i) * t.N + t.tn * 128 + n4 * 4);
; }
; template <class F>
; __device__ __forceinline__ void transpose_tiles(KParams p, LAS unsigned char* lds, int n_it, const F& tile_of) {
;     const int tid = tid_o();
;     LAS float* tile = (LAS float*)lds;
;     if (n_it <= 0) return;
;     f32x4 v[8];
;     TTile cur = tile_desc(p, tile_of(0));
;     tile_load(v, cur, tid);
;     for (int it = 0; it < n_it; ++it) {
;         { const int kr = tid >> 5, n4 = tid & 31;
; #pragma unroll
;           for (int i = 0; i < 8; ++i) { LAS float* t = tile + (kr + 16 * i) * 129 + n4 * 4; t[0] = v[i][0]; t[1] = v[i][1]; t[2] = v[i][2]; t[3] = v[i][3]; } }
.LBB0_374:
	v_lshlrev_b32_e32 v0, 2, v34
	s_lshr_b32 s38, s25, 7
	v_and_b32_e32 v46, 0x7c, v0
	v_cvt_f32_i32_e32 v0, s38
	s_mul_hi_i32 s24, s24, 0x2e8ba2e9
	s_lshr_b32 s28, s24, 31
	s_ashr_i32 s24, s24, 5
	s_add_i32 s24, s24, s28
	s_sext_i32_i16 s28, s40
	v_cvt_f32_i32_e32 v2, s28
	v_rcp_iflag_f32_e32 v3, v0
	s_ashr_i32 s28, s28, 30
	s_or_b32 s39, s28, 1
	v_ashrrev_i32_e32 v36, 5, v34
	v_mul_f32_e32 v3, v2, v3
	v_trunc_f32_e32 v3, v3
	v_fma_f32 v2, -v3, v0, v2
	v_cvt_i32_f32_e32 v3, v3
	v_cmp_ge_f32_e64 s[28:29], |v2|, v0
	s_and_b64 s[28:29], s[28:29], exec
	s_cselect_b32 s28, s39, 0
	v_readfirstlane_b32 s29, v3
	s_add_i32 s39, s29, s28
	s_sext_i32_i16 s43, s39
	v_add_u32_e32 v43, 0x70, v36
	s_lshl_b32 s44, s43, 7
	v_add_u32_e32 v0, s44, v43
	v_mad_u64_u32 v[2:3], s[28:29], v0, s25, 0
	v_ashrrev_i32_e32 v4, 31, v0
	v_mov_b32_e32 v0, v3
	v_add_u32_e32 v42, 0x60, v36
	v_mad_u64_u32 v[4:5], s[28:29], v4, s25, v[0:1]
	s_mul_i32 s39, s39, s38
	v_mov_b32_e32 v3, v4
	s_sub_i32 s28, s40, s39
	v_add_u32_e32 v4, s44, v42
	s_sext_i32_i16 s42, s28
	v_ashrrev_i32_e32 v7, 31, v4
	v_mad_u64_u32 v[4:5], s[40:41], v4, s25, 0
	s_lshl_b32 s28, s42, 7
	v_mov_b32_e32 v6, v5
	s_ashr_i32 s29, s28, 31
	v_mad_u64_u32 v[6:7], s[40:41], v7, s25, v[6:7]
	v_lshl_add_u64 v[2:3], v[2:3], 2, s[10:11]
	s_lshl_b64 s[28:29], s[28:29], 2
	v_mov_b32_e32 v5, v6
	v_lshl_add_u64 v[2:3], v[2:3], 0, s[28:29]
	v_lshlrev_b32_e32 v0, 2, v46
	v_lshl_add_u64 v[4:5], v[4:5], 2, s[10:11]
	v_add_u32_e32 v41, 0x50, v36
	v_lshl_add_u64 v[2:3], v[2:3], 0, v[0:1]
	v_lshl_add_u64 v[4:5], v[4:5], 0, s[28:29]
	v_lshl_add_u64 v[4:5], v[4:5], 0, v[0:1]
	global_load_dwordx4 v[30:33], v[2:3], off
	global_load_dwordx4 v[26:29], v[4:5], off
	v_add_u32_e32 v2, s44, v41
	v_ashrrev_i32_e32 v5, 31, v2
	v_mad_u64_u32 v[2:3], s[40:41], v2, s25, 0
	v_mov_b32_e32 v4, v3
	v_add_u32_e32 v40, 64, v36
	v_mad_u64_u32 v[4:5], s[40:41], v5, s25, v[4:5]
	v_mov_b32_e32 v3, v4
	v_add_u32_e32 v4, s44, v40
	v_ashrrev_i32_e32 v7, 31, v4
	v_mad_u64_u32 v[4:5], s[40:41], v4, s25, 0
	v_mov_b32_e32 v6, v5
	v_mad_u64_u32 v[6:7], s[40:41], v7, s25, v[6:7]
	v_lshl_add_u64 v[2:3], v[2:3], 2, s[10:11]
	v_mov_b32_e32 v5, v6
	v_lshl_add_u64 v[2:3], v[2:3], 0, s[28:29]
	v_lshl_add_u64 v[4:5], v[4:5], 2, s[10:11]
	v_add_u32_e32 v39, 48, v36
	v_lshl_add_u64 v[2:3], v[2:3], 0, v[0:1]
	v_lshl_add_u64 v[4:5], v[4:5], 0, s[28:29]
	v_lshl_add_u64 v[4:5], v[4:5], 0, v[0:1]
	global_load_dwordx4 v[22:25], v[2:3], off
	global_load_dwordx4 v[18:21], v[4:5], off
	v_add_u32_e32 v2, s44, v39
	v_ashrrev_i32_e32 v5, 31, v2
	v_mad_u64_u32 v[2:3], s[40:41], v2, s25, 0
	v_mov_b32_e32 v4, v3
	v_add_u32_e32 v38, 32, v36
	v_mad_u64_u32 v[4:5], s[40:41], v5, s25, v[4:5]
	v_mov_b32_e32 v3, v4
	v_add_u32_e32 v4, s44, v38
	v_ashrrev_i32_e32 v7, 31, v4
	v_mad_u64_u32 v[4:5], s[40:41], v4, s25, 0
	v_mov_b32_e32 v6, v5
	v_mad_u64_u32 v[6:7], s[40:41], v7, s25, v[6:7]
	v_lshl_add_u64 v[2:3], v[2:3], 2, s[10:11]
	v_mov_b32_e32 v5, v6
	v_lshl_add_u64 v[2:3], v[2:3], 0, s[28:29]
	v_lshl_add_u64 v[4:5], v[4:5], 2, s[10:11]
	v_add_u32_e32 v37, 16, v36
	v_lshl_add_u64 v[2:3], v[2:3], 0, v[0:1]
	v_lshl_add_u64 v[4:5], v[4:5], 0, s[28:29]
	v_lshl_add_u64 v[4:5], v[4:5], 0, v[0:1]
	global_load_dwordx4 v[14:17], v[2:3], off
	global_load_dwordx4 v[10:13], v[4:5], off
	v_add_u32_e32 v2, s44, v37
	v_ashrrev_i32_e32 v5, 31, v2
	v_mad_u64_u32 v[2:3], s[40:41], v2, s25, 0
	v_mov_b32_e32 v4, v3
	v_mad_u64_u32 v[4:5], s[40:41], v5, s25, v[4:5]
	v_mov_b32_e32 v3, v4
	v_add_u32_e32 v4, s44, v36
	v_ashrrev_i32_e32 v7, 31, v4
	v_mad_u64_u32 v[4:5], s[40:41], v4, s25, 0
	v_mov_b32_e32 v6, v5
	v_mad_u64_u32 v[6:7], s[40:41], v7, s25, v[6:7]
	v_mov_b32_e32 v5, v6
	v_lshl_add_u64 v[2:3], v[2:3], 2, s[10:11]
	v_lshl_add_u64 v[4:5], v[4:5], 2, s[10:11]
	v_lshl_add_u64 v[2:3], v[2:3], 0, s[28:29]
	v_lshl_add_u64 v[4:5], v[4:5], 0, s[28:29]
	v_lshl_add_u64 v[2:3], v[2:3], 0, v[0:1]
	v_lshl_add_u64 v[4:5], v[4:5], 0, v[0:1]
	global_load_dwordx4 v[6:9], v[2:3], off
	s_nop 0
	global_load_dwordx4 v[2:5], v[4:5], off
	s_mul_i32 s9, s9, 0x6200000
	s_mul_hi_u32 s10, s8, 0x6200000
	s_add_i32 s10, s10, s9
	s_mul_i32 s8, s8, 0x6200000
	s_waitcnt lgkmcnt(0)
	s_add_u32 s11, s48, s8
	s_addc_u32 s10, s49, s10
	s_lshl_b64 s[8:9], s[26:27], 1
	s_add_u32 s8, s11, s8
	v_ashrrev_i32_e32 v44, 4, v34
	v_lshlrev_b32_e32 v34, 3, v34
	s_addc_u32 s9, s10, s9
	v_and_b32_e32 v34, 0x78, v34
	s_movk_i32 s10, 0x204
	v_add_u32_e32 v0, 0, v0
	v_lshl_add_u32 v35, v44, 2, 0
	v_mul_u32_u24_e32 v47, 0x204, v34
	v_mul_lo_u32 v45, v36, s10
	s_mov_b32 s25, 0
	s_addk_i32 s30, 0xca0
	v_add_u32_e32 v45, v0, v45
	v_lshlrev_b32_e32 v0, 2, v46
	v_lshlrev_b32_e32 v34, 1, v34
	v_add_u32_e32 v46, v35, v47
	s_mov_b64 s[10:11], s[8:9]
	s_mov_b32 s44, s13
	s_mov_b32 s40, s43
	s_mov_b32 s41, s42
	s_branch .LBB0_377

; #define LAS __attribute__((address_space(3)))
; __device__ __forceinline__ int tid_o() { int t = (int)threadIdx.x; asm volatile("" : "+v"(t)); return t; }
; __device__ __forceinline__ int bid_o() { int t = (int)blockIdx.x; asm volatile("" : "+s"(t)); return t; }
; __device__ __forceinline__ float silu_f(float x) { return x * __builtin_amdgcn_rcpf(1.0f + __expf(-x)); }
; __device__ void ada_prep(KParams p, LAS unsigned char* lds) {
;     LAS float* sc = (LAS float*)lds;
;     const int tid = tid_o();
;     for (int i = tid; i < 9 * 2048; i += 512) { const int r = i >> 11, d = i & 2047; const float v = r < 8 ? p->c[r * 2048 + d] : p->c_ctx[d]; sc[i] = silu_f(v); }
;     __syncthreads();
; __device__ void prepass(KParams p, LAS unsigned char* lds) {
;     const int tid = tid_o(), bid = bid_o();
;     if (bid < 192) { ada_prep(p, lds); ada_item(p, bid, lds); }
;     const int n_it = bid < 192 ? 14 : 24;
.LBB0_406:
	v_mov_b32_e32 v0, v208
	s_mov_b32 s26, s94
	s_cmpk_gt_i32 s26, 0xbf
	s_mov_b32 s27, 17
	s_cbranch_scc1 .LBB0_422
	s_waitcnt vmcnt(8)
	v_mov_b32_e32 v2, v208
	s_movk_i32 s8, 0x4800
	s_nop 0
	v_cmp_gt_i32_e32 vcc, s8, v2
	s_and_saveexec_b64 s[8:9], vcc
	s_cbranch_execz .LBB0_414
	v_ashrrev_i32_e32 v3, 31, v2
	v_lshlrev_b64 v[4:5], 2, v[2:3]
	v_lshl_add_u32 v3, v2, 2, 0
	s_mov_b64 s[10:11], 0
	s_branch .LBB0_410

; __device__ __forceinline__ float silu_f(float x) { return x * __builtin_amdgcn_rcpf(1.0f + __expf(-x)); }
; __device__ void ada_prep(KParams p, LAS unsigned char* lds) {
;     ...
;     for (int i = tid; i < 9 * 2048; i += 512) { const int r = i >> 11, d = i & 2047; const float v = r < 8 ? p->c[r * 2048 + d] : p->c_ctx[d]; sc[i] = silu_f(v); }
;     __syncthreads();
; __device__ void prepass(KParams p, LAS unsigned char* lds) {
;     ...
;     if (bid < 192) { ada_prep(p, lds); ada_item(p, bid, lds); }
;     const int n_it = bid < 192 ? 14 : 24;
.LBB0_421:
	s_or_b64 exec, exec, s[8:9]
	s_mov_b32 s27, 8
	s_barrier

; #define LAS __attribute__((address_space(3)))
; __device__ __forceinline__ int tid_o() { int t = (int)threadIdx.x; asm volatile("" : "+v"(t)); return t; }
; template <class F>
; __device__ __forceinline__ void transpose_tiles(KParams p, LAS unsigned char* lds, int n_it, const F& tile_of) {
;     const int tid = tid_o();
;     LAS float* tile = (LAS float*)lds;
;     if (n_it <= 0) return;
;     f32x4 v[8];
;     TTile cur = tile_desc(p, tile_of(0));
;     tile_load(v, cur, tid);
;     for (int it = 0; it < n_it; ++it) {
;         { const int kr = tid >> 5, n4 = tid & 31;
; #pragma unroll
;           for (int i = 0; i < 8; ++i) { LAS float* t = tile + (kr + 16 * i) * 129 + n4 * 4; t[0] = v[i][0]; t[1] = v[i][1]; t[2] = v[i][2]; t[3] = v[i][3]; } }
;         TTile nxt = cur;
;         if (it + 1 < n_it) { nxt = tile_desc(p, tile_of(it + 1)); tile_load(v, nxt, tid); }
; __device__ void prepass(KParams p, LAS unsigned char* lds) {
;     ...
;     auto tile_of = [&](int k) { return k < 14 ? k * 256 + bid : 3584 + (k - 14) * 64 + (bid - 192); };
.LBB0_433:
	s_lshr_b32 s29, s28, 7
	v_cvt_f32_i32_e32 v0, s29
	s_sext_i32_i16 s8, s40
	s_waitcnt vmcnt(8)
	v_cvt_f32_i32_e32 v2, s8
	s_ashr_i32 s8, s8, 30
	v_rcp_iflag_f32_e32 v3, v0
	s_or_b32 s38, s8, 1
	s_mul_i32 s11, s11, 0x6200000
	v_ashrrev_i32_e32 v37, 5, v34
	v_mul_f32_e32 v3, v2, v3
	v_trunc_f32_e32 v3, v3
	v_fma_f32 v2, -v3, v0, v2
	v_cvt_i32_f32_e32 v3, v3
	v_cmp_ge_f32_e64 s[8:9], |v2|, v0
	s_and_b64 s[8:9], s[8:9], exec
	s_cselect_b32 s8, s38, 0
	v_readfirstlane_b32 s9, v3
	s_add_i32 s8, s9, s8
	s_sext_i32_i16 s44, s8
	s_mul_i32 s8, s8, s29
	s_sub_i32 s8, s40, s8
	s_sext_i32_i16 s46, s8
	s_load_dwordx2 s[8:9], s[0:1], 0xa8
	s_mul_hi_u32 s29, s10, 0x6200000
	s_add_i32 s29, s29, s11
	s_mul_i32 s10, s10, 0x6200000
	v_lshlrev_b32_e32 v0, 2, v34
	s_waitcnt lgkmcnt(0)
	s_add_u32 s38, s8, s10
	s_addc_u32 s29, s9, s29
	s_lshl_b64 s[10:11], s[24:25], 1
	s_add_u32 s10, s38, s10
	s_addc_u32 s11, s29, s11
	s_lshl_b32 s29, s44, 7
	v_add_u32_e32 v40, 32, v37
	v_add_u32_e32 v45, 64, v37
	v_add_u32_e32 v47, 0x60, v37
	v_and_b32_e32 v50, 0x7c, v0
	v_add_u32_e32 v0, s29, v37
	v_add_u32_e32 v10, s29, v40
	s_waitcnt vmcnt(7)
	v_add_u32_e32 v18, s29, v45
	s_waitcnt vmcnt(5)
	v_add_u32_e32 v26, s29, v47
	v_mad_u64_u32 v[2:3], s[24:25], v0, s28, 0
	v_ashrrev_i32_e32 v13, 31, v10
	v_mad_u64_u32 v[10:11], s[40:41], v10, s28, 0
	v_ashrrev_i32_e32 v21, 31, v18
	v_mad_u64_u32 v[18:19], s[40:41], v18, s28, 0
	v_ashrrev_i32_e32 v29, 31, v26
	v_mad_u64_u32 v[26:27], s[40:41], v26, s28, 0
	v_ashrrev_i32_e32 v4, 31, v0
	v_mov_b32_e32 v0, v3
	v_mov_b32_e32 v12, v11
	v_mov_b32_e32 v20, v19
	v_mov_b32_e32 v28, v27
	v_mad_u64_u32 v[4:5], s[24:25], v4, s28, v[0:1]
	v_add_u32_e32 v39, 16, v37
	v_mad_u64_u32 v[12:13], s[40:41], v13, s28, v[12:13]
	v_add_u32_e32 v43, 48, v37
	v_mad_u64_u32 v[20:21], s[40:41], v21, s28, v[20:21]
	v_add_u32_e32 v46, 0x50, v37
	v_mad_u64_u32 v[28:29], s[40:41], v29, s28, v[28:29]
	v_add_u32_e32 v48, 0x70, v37
	v_mov_b32_e32 v3, v4
	v_add_u32_e32 v4, s29, v39
	v_mov_b32_e32 v11, v12
	v_add_u32_e32 v12, s29, v43
	v_mov_b32_e32 v19, v20
	v_add_u32_e32 v20, s29, v46
	v_mov_b32_e32 v27, v28
	v_add_u32_e32 v28, s29, v48
	v_ashrrev_i32_e32 v7, 31, v4
	v_mad_u64_u32 v[4:5], s[40:41], v4, s28, 0
	v_ashrrev_i32_e32 v15, 31, v12
	v_mad_u64_u32 v[12:13], s[40:41], v12, s28, 0
	v_ashrrev_i32_e32 v23, 31, v20
	v_mad_u64_u32 v[20:21], s[40:41], v20, s28, 0
	s_waitcnt vmcnt(4)
	v_ashrrev_i32_e32 v31, 31, v28
	v_mad_u64_u32 v[28:29], s[40:41], v28, s28, 0
	v_mov_b32_e32 v6, v5
	v_mov_b32_e32 v14, v13
	v_mov_b32_e32 v22, v21
	v_mov_b32_e32 v30, v29
	s_lshl_b32 s24, s46, 7
	v_mad_u64_u32 v[6:7], s[40:41], v7, s28, v[6:7]
	v_mad_u64_u32 v[14:15], s[40:41], v15, s28, v[14:15]
	v_mad_u64_u32 v[22:23], s[40:41], v23, s28, v[22:23]
	v_mad_u64_u32 v[30:31], s[28:29], v31, s28, v[30:31]
	s_ashr_i32 s25, s24, 31
	v_mov_b32_e32 v5, v6
	v_mov_b32_e32 v13, v14
	v_mov_b32_e32 v21, v22
	v_mov_b32_e32 v29, v30
	v_lshl_add_u64 v[2:3], v[2:3], 2, s[12:13]
	s_lshl_b64 s[24:25], s[24:25], 2
	v_lshl_add_u64 v[4:5], v[4:5], 2, s[12:13]
	v_lshl_add_u64 v[10:11], v[10:11], 2, s[12:13]
	v_lshl_add_u64 v[12:13], v[12:13], 2, s[12:13]
	v_lshl_add_u64 v[18:19], v[18:19], 2, s[12:13]
	v_lshl_add_u64 v[20:21], v[20:21], 2, s[12:13]
	v_lshl_add_u64 v[26:27], v[26:27], 2, s[12:13]
	v_lshl_add_u64 v[28:29], v[28:29], 2, s[12:13]
	v_lshl_add_u64 v[2:3], v[2:3], 0, s[24:25]
	v_lshlrev_b32_e32 v0, 2, v50
	v_lshl_add_u64 v[4:5], v[4:5], 0, s[24:25]
	v_lshl_add_u64 v[10:11], v[10:11], 0, s[24:25]
	v_lshl_add_u64 v[12:13], v[12:13], 0, s[24:25]
	v_lshl_add_u64 v[18:19], v[18:19], 0, s[24:25]
	v_lshl_add_u64 v[20:21], v[20:21], 0, s[24:25]
	v_lshl_add_u64 v[26:27], v[26:27], 0, s[24:25]
	v_lshl_add_u64 v[28:29], v[28:29], 0, s[24:25]
	v_lshl_add_u64 v[2:3], v[2:3], 0, v[0:1]
	v_lshl_add_u64 v[4:5], v[4:5], 0, v[0:1]
	v_lshl_add_u64 v[10:11], v[10:11], 0, v[0:1]
	v_lshl_add_u64 v[12:13], v[12:13], 0, v[0:1]
	v_lshl_add_u64 v[18:19], v[18:19], 0, v[0:1]
	v_lshl_add_u64 v[20:21], v[20:21], 0, v[0:1]
	v_lshl_add_u64 v[26:27], v[26:27], 0, v[0:1]
	v_lshl_add_u64 v[28:29], v[28:29], 0, v[0:1]
	global_load_dwordx4 v[6:9], v[2:3], off
	s_nop 0
	global_load_dwordx4 v[2:5], v[4:5], off
	s_nop 0
	global_load_dwordx4 v[14:17], v[10:11], off
	s_nop 0
	global_load_dwordx4 v[10:13], v[12:13], off
	s_nop 0
	global_load_dwordx4 v[22:25], v[18:19], off
	s_nop 0
	global_load_dwordx4 v[18:21], v[20:21], off
	s_nop 0
	global_load_dwordx4 v[30:33], v[26:27], off
	s_nop 0
	global_load_dwordx4 v[26:29], v[28:29], off
	v_add_u32_e32 v35, 0, v0
	v_lshlrev_b32_e32 v0, 3, v34
	v_ashrrev_i32_e32 v44, 4, v34
	v_and_b32_e32 v0, 0x78, v0
	s_movk_i32 s12, 0x204
	v_lshl_add_u32 v41, v44, 2, 0
	v_mul_u32_u24_e32 v51, 0x204, v0
	v_mul_lo_u32 v49, v37, s12
	s_mov_b32 s40, 0
	v_add_u32_e32 v36, 0x60, v44
	v_add_u32_e32 v42, 32, v44
	v_add_u32_e32 v38, 64, v44
	s_add_i32 s41, s27, 1
	s_add_i32 s42, s26, 0x700
	s_add_i32 s43, s26, 0x100
	v_lshlrev_b32_e32 v34, 2, v50
	v_lshlrev_b32_e32 v0, 1, v0
	v_add_u32_e32 v49, v35, v49
	v_add_u32_e32 v41, v41, v51
.LBB0_434:
	s_cmp_lt_u32 s40, 9
	s_cselect_b32 s13, s43, s42
	s_mul_hi_i32 s12, s13, 0x5397829d
	s_lshr_b32 s24, s12, 31
	s_ashr_i32 s12, s12, 10
	s_add_i32 s12, s12, s24
	s_mul_i32 s24, s12, 0xc40
	s_sub_i32 s47, s13, s24
	v_add_u32_e32 v50, 0x2040, v49
	v_add_u32_e32 v51, 0x2048, v49
	v_add_u32_e32 v52, 0x4080, v49
	v_add_u32_e32 v53, 0x4088, v49
	v_add_u32_e32 v54, 0x60c0, v49
	v_add_u32_e32 v55, 0x60c8, v49
	v_add_u32_e32 v56, 0x8100, v49
	v_add_u32_e32 v57, 0x8108, v49
	v_add_u32_e32 v58, 0xa140, v49
	v_add_u32_e32 v59, 0xa148, v49
	v_add_u32_e32 v60, 0xc180, v49
	v_add_u32_e32 v61, 0xc188, v49
	v_add_u32_e32 v62, 0xe1c0, v49
	v_add_u32_e32 v63, 0xe1c8, v49
	s_cmpk_gt_i32 s47, 0x33f
	s_mov_b64 s[28:29], -1
	s_waitcnt vmcnt(7)
	ds_write2_b32 v49, v6, v7 offset1:1
	ds_write2_b32 v49, v8, v9 offset0:2 offset1:3
	s_waitcnt vmcnt(6)
	ds_write2_b32 v50, v2, v3 offset1:1
	ds_write2_b32 v51, v4, v5 offset1:1
	s_waitcnt vmcnt(5)
	ds_write2_b32 v52, v14, v15 offset1:1
	ds_write2_b32 v53, v16, v17 offset1:1
	s_waitcnt vmcnt(4)
	ds_write2_b32 v54, v10, v11 offset1:1
	ds_write2_b32 v55, v12, v13 offset1:1
	s_waitcnt vmcnt(3)
	ds_write2_b32 v56, v22, v23 offset1:1
	ds_write2_b32 v57, v24, v25 offset1:1
	s_waitcnt vmcnt(2)
	ds_write2_b32 v58, v18, v19 offset1:1
	ds_write2_b32 v59, v20, v21 offset1:1
	s_waitcnt vmcnt(1)
	ds_write2_b32 v60, v30, v31 offset1:1
	ds_write2_b32 v61, v32, v33 offset1:1
	s_waitcnt vmcnt(0)
	ds_write2_b32 v62, v26, v27 offset1:1
	ds_write2_b32 v63, v28, v29 offset1:1
	s_cbranch_scc0 .LBB0_443
	s_cmpk_gt_u32 s47, 0x43f
	s_cbranch_scc0 .LBB0_440
	s_ashr_i32 s13, s12, 31
	s_lshl_b64 s[28:29], s[12:13], 26
	s_cmpk_gt_u32 s47, 0x83f
	s_mov_b64 s[24:25], -1
	s_cbranch_scc0 .LBB0_438
	s_load_dwordx2 s[24:25], s[0:1], 0x88
	s_add_i32 s49, s47, 0xfffff7c0
	s_waitcnt lgkmcnt(0)
	s_add_u32 s26, s24, s28
	s_addc_u32 s27, s25, s29
	s_mov_b64 s[24:25], 0
